# v56 + hg_pass2 decay table copied to LDS with 16 loads in flight
# speedup vs baseline: 1.0137x; 1.0019x over previous
; #define LAS __attribute__((address_space(3)))
; __device__ __forceinline__ void hg_pass2(Frame& F) {
;     ...
;         for (int i = F.tid; i < 256 * 32; i += 512) { const int c = i >> 5, d4 = (i & 31) * 4; *(LAS f32x4*)(AD + c * 128 + d4) = *(const f32x4*)(ADEC + ((size_t)c * 16 + h) * 128 + d4); }
;         __syncthreads();
.LBB0_734:
	global_load_dwordx4 v[58:61], v[16:17], off
	v_lshl_add_u64 v[16:17], v[16:17], 0, s[54:55]
	global_load_dwordx4 v[84:87], v[16:17], off
	v_lshl_add_u64 v[16:17], v[16:17], 0, s[54:55]
	global_load_dwordx4 v[88:91], v[16:17], off
	v_lshl_add_u64 v[16:17], v[16:17], 0, s[54:55]
	global_load_dwordx4 v[92:95], v[16:17], off
	v_lshl_add_u64 v[16:17], v[16:17], 0, s[54:55]
	global_load_dwordx4 v[96:99], v[16:17], off
	v_lshl_add_u64 v[16:17], v[16:17], 0, s[54:55]
	global_load_dwordx4 v[100:103], v[16:17], off
	v_lshl_add_u64 v[16:17], v[16:17], 0, s[54:55]
	global_load_dwordx4 v[104:107], v[16:17], off
	v_lshl_add_u64 v[16:17], v[16:17], 0, s[54:55]
	global_load_dwordx4 v[108:111], v[16:17], off
	v_lshl_add_u64 v[16:17], v[16:17], 0, s[54:55]
	global_load_dwordx4 v[112:115], v[16:17], off
	v_lshl_add_u64 v[16:17], v[16:17], 0, s[54:55]
	global_load_dwordx4 v[116:119], v[16:17], off
	v_lshl_add_u64 v[16:17], v[16:17], 0, s[54:55]
	global_load_dwordx4 v[120:123], v[16:17], off
	v_lshl_add_u64 v[16:17], v[16:17], 0, s[54:55]
	global_load_dwordx4 v[124:127], v[16:17], off
	v_lshl_add_u64 v[16:17], v[16:17], 0, s[54:55]
	global_load_dwordx4 v[128:131], v[16:17], off
	v_lshl_add_u64 v[16:17], v[16:17], 0, s[54:55]
	global_load_dwordx4 v[132:135], v[16:17], off
	v_lshl_add_u64 v[16:17], v[16:17], 0, s[54:55]
	global_load_dwordx4 v[136:139], v[16:17], off
	v_lshl_add_u64 v[16:17], v[16:17], 0, s[54:55]
	global_load_dwordx4 v[140:143], v[16:17], off
	s_waitcnt vmcnt(15)
	ds_write_b128 v19, v[58:61]
	v_add_u32_e32 v19, 0x2000, v19
	s_waitcnt vmcnt(14)
	ds_write_b128 v19, v[84:87]
	v_add_u32_e32 v19, 0x2000, v19
	s_waitcnt vmcnt(13)
	ds_write_b128 v19, v[88:91]
	v_add_u32_e32 v19, 0x2000, v19
	s_waitcnt vmcnt(12)
	ds_write_b128 v19, v[92:95]
	v_add_u32_e32 v19, 0x2000, v19
	s_waitcnt vmcnt(11)
	ds_write_b128 v19, v[96:99]
	v_add_u32_e32 v19, 0x2000, v19
	s_waitcnt vmcnt(10)
	ds_write_b128 v19, v[100:103]
	v_add_u32_e32 v19, 0x2000, v19
	s_waitcnt vmcnt(9)
	ds_write_b128 v19, v[104:107]
	v_add_u32_e32 v19, 0x2000, v19
	s_waitcnt vmcnt(8)
	ds_write_b128 v19, v[108:111]
	v_add_u32_e32 v19, 0x2000, v19
	s_waitcnt vmcnt(7)
	ds_write_b128 v19, v[112:115]
	v_add_u32_e32 v19, 0x2000, v19
	s_waitcnt vmcnt(6)
	ds_write_b128 v19, v[116:119]
	v_add_u32_e32 v19, 0x2000, v19
	s_waitcnt vmcnt(5)
	ds_write_b128 v19, v[120:123]
	v_add_u32_e32 v19, 0x2000, v19
	s_waitcnt vmcnt(4)
	ds_write_b128 v19, v[124:127]
	v_add_u32_e32 v19, 0x2000, v19
	s_waitcnt vmcnt(3)
	ds_write_b128 v19, v[128:131]
	v_add_u32_e32 v19, 0x2000, v19
	s_waitcnt vmcnt(2)
	ds_write_b128 v19, v[132:135]
	v_add_u32_e32 v19, 0x2000, v19
	s_waitcnt vmcnt(1)
	ds_write_b128 v19, v[136:139]
	v_add_u32_e32 v19, 0x2000, v19
	s_waitcnt vmcnt(0)
	ds_write_b128 v19, v[140:143]
	s_or_b64 exec, exec, s[14:15]
	v_lshlrev_b32_e32 v16, 2, v38
	v_and_b32_e32 v16, 0x7f00, v16
	s_lshl_b64 s[12:13], s[12:13], 15
	v_or_b32_e32 v16, s12, v16
	v_mov_b32_e32 v17, s13
	v_mov_b32_e32 v18, 0
	v_lshl_add_u64 v[16:17], v[12:13], 0, v[16:17]
	s_mov_b32 s12, -16
	v_mov_b32_e32 v53, v3
	v_mov_b32_e32 v19, v18
	s_waitcnt lgkmcnt(0)
	s_barrier
